# context-row (64x128 tile) residual epilogues of the N=1024 GEMMs: all 16 gate/x loads issued before the first wait (was 8 serial round trips, on the phase's critical path); on top of v38
# baseline (speedup 1.0000x reference)
; __device__ __forceinline__ f32x4 mfma16(bf16x8 a, bf16x8 b, f32x4 c) { return __builtin_amdgcn_mfma_f32_16x16x32_bf16(a, b, c, 0, 0, 0); }
;     ...
;     for (int kt = 0; kt < nk; ++kt) {
;         lds_sync();
; #pragma unroll
;         for (int i = 0; i < 4; ++i) *(u32x4*)(sW + (srow + i * 32) * GST + skc) = rw[i];
;         lds_sync();
;         const int k0 = (kt + 1 < nk ? kt + 1 : kt) << 6;
;         const int ka = FRAG ? (k0 >> 5) * 512 : k0;
; #pragma unroll
;         for (int i = 0; i < 4; ++i) rw[i] = *(const u32x4*)(wp + (size_t)(i * 32) * ldw + k0);
;         bf16x8 wa[4], wb[4];
; #pragma unroll
;         for (int j = 0; j < 4; ++j) wa[j] = lds16(wr + (j * 16) * GST);
; #pragma unroll
;         for (int j = 0; j < 4; ++j) wb[j] = lds16(wr + ((j + 4) * 16) * GST);
;         __builtin_amdgcn_sched_barrier(0);
;         __builtin_amdgcn_s_setprio(1);
; #pragma unroll
;         for (int j = 0; j < 4; ++j)
; #pragma unroll
;             for (int i = 0; i < MI; ++i) acc[i][j] = mfma16(wa[j], __builtin_bit_cast(bf16x8, ra[i][0]), acc[i][j]);
;         __builtin_amdgcn_sched_barrier(0);
; #pragma unroll
;         for (int j = 0; j < 4; ++j) wa[j] = lds16(wr + (j * 16) * GST + 32);
;         __builtin_amdgcn_sched_barrier(0);
; #pragma unroll
;         for (int j = 0; j < 4; ++j)
; #pragma unroll
;             for (int i = 0; i < MI; ++i) acc[i][j + 4] = mfma16(wb[j], __builtin_bit_cast(bf16x8, ra[i][0]), acc[i][j + 4]);
;         __builtin_amdgcn_sched_barrier(0);
; #pragma unroll
;         for (int i = 0; i < MI; ++i) ra[i][0] = *(const u32x4*)(ap + (size_t)i * ASI + ka);
; #pragma unroll
;         for (int j = 0; j < 4; ++j) wb[j] = lds16(wr + ((j + 4) * 16) * GST + 32);
;         __builtin_amdgcn_sched_barrier(0);
; #pragma unroll
;         for (int j = 0; j < 4; ++j)
; #pragma unroll
;             for (int i = 0; i < MI; ++i) acc[i][j] = mfma16(wa[j], __builtin_bit_cast(bf16x8, ra[i][1]), acc[i][j]);
;         __builtin_amdgcn_sched_barrier(0);
; #pragma unroll
;         for (int j = 0; j < 4; ++j)
; #pragma unroll
;             for (int i = 0; i < MI; ++i) acc[i][j + 4] = mfma16(wb[j], __builtin_bit_cast(bf16x8, ra[i][1]), acc[i][j + 4]);
;         __builtin_amdgcn_s_setprio(0);
;         __builtin_amdgcn_sched_barrier(0);
; #pragma unroll
;         for (int i = 0; i < MI; ++i) ra[i][1] = *(const u32x4*)(ap + (size_t)i * ASI + ka + ASK);
;     }
.LBB0_189:
	s_cmpk_lg_i32 s5, 0x400
	s_cselect_b32 s78, s5, 0x3c0
	s_waitcnt vmcnt(63) expcnt(7) lgkmcnt(15)
	s_barrier
	s_waitcnt vmcnt(3)
	ds_write_b128 v61, v[48:51]
	s_waitcnt vmcnt(1)
	ds_write_b128 v61, v[52:55] offset:4608
	ds_write_b128 v61, v[40:43] offset:9216
	ds_write_b128 v61, v[44:47] offset:13824
	v_lshl_add_u64 v[40:41], s[78:79], 1, v[56:57]
	v_add_co_u32_e32 v42, vcc, s97, v40
	s_waitcnt lgkmcnt(0)
	s_nop 0
	v_addc_co_u32_e32 v43, vcc, 0, v41, vcc
	v_add_co_u32_e32 v44, vcc, s80, v40
	s_barrier
	s_nop 0
	v_addc_co_u32_e32 v45, vcc, 0, v41, vcc
	v_add_co_u32_e32 v46, vcc, s86, v40
	s_nop 1
	v_addc_co_u32_e32 v47, vcc, 0, v41, vcc
	global_load_dwordx4 v[48:51], v[40:41], off
	global_load_dwordx4 v[52:55], v[42:43], off
	s_nop 0
	global_load_dwordx4 v[40:43], v[44:45], off
	s_nop 0
	global_load_dwordx4 v[44:47], v[46:47], off
	ds_read_b128 v[62:65], v60
	ds_read_b128 v[66:69], v60 offset:2304
	ds_read_b128 v[70:73], v60 offset:4608
	ds_read_b128 v[74:77], v60 offset:6912
	ds_read_b128 v[78:81], v60 offset:9216
	ds_read_b128 v[82:85], v60 offset:11520
	ds_read_b128 v[86:89], v60 offset:13824
	ds_read_b128 v[90:93], v60 offset:16128
	s_setprio 1
	s_waitcnt lgkmcnt(7)
	v_mfma_f32_16x16x32_bf16 v[28:31], v[62:65], v[36:39], v[28:31]
	s_waitcnt lgkmcnt(6)
	v_mfma_f32_16x16x32_bf16 v[24:27], v[66:69], v[36:39], v[24:27]
	s_waitcnt lgkmcnt(5)
	v_mfma_f32_16x16x32_bf16 v[20:23], v[70:73], v[36:39], v[20:23]
	s_waitcnt lgkmcnt(4)
	v_mfma_f32_16x16x32_bf16 v[16:19], v[74:77], v[36:39], v[16:19]
	ds_read_b128 v[62:65], v60 offset:64
	ds_read_b128 v[66:69], v60 offset:2368
	ds_read_b128 v[70:73], v60 offset:4672
	ds_read_b128 v[74:77], v60 offset:6976
	s_waitcnt lgkmcnt(7)
	v_mfma_f32_16x16x32_bf16 v[12:15], v[78:81], v[36:39], v[12:15]
	s_waitcnt lgkmcnt(6)
	v_mfma_f32_16x16x32_bf16 v[8:11], v[82:85], v[36:39], v[8:11]
	s_waitcnt lgkmcnt(5)
	v_mfma_f32_16x16x32_bf16 v[4:7], v[86:89], v[36:39], v[4:7]
	s_waitcnt lgkmcnt(4)
	v_mfma_f32_16x16x32_bf16 v[0:3], v[90:93], v[36:39], v[0:3]
	s_lshl_b32 s78, s78, 5
	v_lshl_add_u64 v[94:95], v[58:59], 0, s[78:79]
	global_load_dwordx4 v[36:39], v[94:95], off
	ds_read_b128 v[78:81], v60 offset:9280
	ds_read_b128 v[82:85], v60 offset:11584
	ds_read_b128 v[86:89], v60 offset:13888
	ds_read_b128 v[90:93], v60 offset:16192
	s_waitcnt vmcnt(5) lgkmcnt(7)
	v_mfma_f32_16x16x32_bf16 v[28:31], v[62:65], v[32:35], v[28:31]
	s_waitcnt lgkmcnt(6)
	v_mfma_f32_16x16x32_bf16 v[24:27], v[66:69], v[32:35], v[24:27]
	s_waitcnt lgkmcnt(5)
	v_mfma_f32_16x16x32_bf16 v[20:23], v[70:73], v[32:35], v[20:23]
	s_waitcnt lgkmcnt(4)
	v_mfma_f32_16x16x32_bf16 v[16:19], v[74:77], v[32:35], v[16:19]
	s_waitcnt lgkmcnt(3)
	v_mfma_f32_16x16x32_bf16 v[12:15], v[78:81], v[32:35], v[12:15]
	s_waitcnt lgkmcnt(2)
	v_mfma_f32_16x16x32_bf16 v[8:11], v[82:85], v[32:35], v[8:11]
	s_waitcnt lgkmcnt(1)
	v_mfma_f32_16x16x32_bf16 v[4:7], v[86:89], v[32:35], v[4:7]
	s_waitcnt lgkmcnt(0)
	v_mfma_f32_16x16x32_bf16 v[0:3], v[90:93], v[32:35], v[0:3]
	s_setprio 0
	global_load_dwordx4 v[32:35], v[94:95], off offset:1024
	s_add_i32 s5, s5, 64
	s_cmpk_lg_i32 s5, 0x440
	s_cbranch_scc1 .LBB0_189
; __device__ __forceinline__ int tid_() { int t = threadIdx.x; asm volatile("" : "+v"(t)); return t; }
; template <int MI>
; __device__ __forceinline__ void epi_resid(CParams& p, int m0, int n0, const f32x4 (&acc)[MI][8], const float* gate  ) {
;     const int lane = tid_() & 63, wave = tid_() >> 6, l16 = lane & 15, quad = lane >> 4;
; #pragma unroll
;     for (int i = 0; i < MI; ++i) {
;         const int row = m0 + wave * 16 * MI + i * 16 + l16;
;         float* xr = xrow(p, row);
;         const float* g = gate + (size_t)seg_of(row) * 6144;
;         float ss = 0.f;
; #pragma unroll
;         for (int j = 0; j < 8; ++j) {
;             const int col = n0 + j * 16 + quad * 4;
;             const f32x4 gv = *(const f32x4*)(g + col);
;             f32x4 xv = *(f32x4*)(xr + col);
;             xv += gv * acc[i][j];
;             *(f32x4*)(xr + col) = xv;
;             ss += xv[0] * xv[0] + xv[1] * xv[1] + xv[2] * xv[2] + xv[3] * xv[3];
;         }
;         ss += __shfl_xor(ss, 16); ss += __shfl_xor(ss, 32);
;         if (quad == 0) ((float*)(p.ws + WS_PART))[(size_t)row * 8 + (n0 >> 7)] = ss;
;         __builtin_amdgcn_sched_barrier(0);
;     }
; }
	s_waitcnt vmcnt(0)
	v_mov_b32_e32 v32, v167
	v_mov_b32_e32 v33, v167
	v_mov_b32_e32 v36, s16
	v_ashrrev_i32_e32 v33, 2, v33
	v_bfe_u32 v40, v32, 4, 2
	v_and_b32_e32 v33, -16, v33
	v_and_or_b32 v32, v32, 15, s4
	v_add_u32_e32 v32, v33, v32
	v_cmp_gt_i32_e64 s[42:43], s34, v32
	v_subrev_co_u32_e32 v34, vcc, 0x4000, v32
	v_ashrrev_i32_e32 v33, 31, v32
	v_mov_b32_e32 v37, s45
	v_cndmask_b32_e64 v35, 0, v33, s[42:43]
	v_cndmask_b32_e64 v34, v34, v32, s[42:43]
	v_cndmask_b32_e64 v37, v36, v37, s[42:43]
	v_mov_b32_e32 v36, s15
	v_mov_b32_e32 v38, s44
	v_cndmask_b32_e64 v36, v36, v38, s[42:43]
	v_lshlrev_b64 v[34:35], 12, v[34:35]
	s_movk_i32 s2, 0x1fff
	v_lshl_add_u64 v[34:35], v[36:37], 0, v[34:35]
	v_cndmask_b32_e32 v36, v213, v214, vcc
	v_cmp_lt_i32_e32 vcc, s2, v32
	s_lshl_b32 s4, s6, 9
	s_nop 0
	v_cndmask_b32_e32 v36, 0, v36, vcc
	v_lshlrev_b32_e32 v164, 2, v36
	v_lshl_add_u64 v[36:37], s[48:49], 0, v[164:165]
	v_cmp_lt_i32_e32 vcc, v204, v199
	v_lshl_or_b32 v164, v40, 4, s4
	v_lshl_add_u64 v[36:37], v[36:37], 0, v[164:165]
	v_cndmask_b32_e32 v38, v197, v204, vcc
	v_cmp_lt_i32_e32 vcc, v205, v199
	v_lshl_add_u64 v[34:35], v[34:35], 0, v[164:165]
	global_load_dwordx4 v[48:51], v[34:35], off
	global_load_dwordx4 v[52:55], v[36:37], off
	global_load_dwordx4 v[56:59], v[36:37], off offset:64
	global_load_dwordx4 v[60:63], v[34:35], off offset:64
	global_load_dwordx4 v[64:67], v[36:37], off offset:128
	global_load_dwordx4 v[68:71], v[34:35], off offset:128
	global_load_dwordx4 v[72:75], v[36:37], off offset:192
	global_load_dwordx4 v[76:79], v[34:35], off offset:192
	global_load_dwordx4 v[80:83], v[36:37], off offset:256
	global_load_dwordx4 v[84:87], v[34:35], off offset:256
	global_load_dwordx4 v[88:91], v[36:37], off offset:320
	global_load_dwordx4 v[92:95], v[34:35], off offset:320
	global_load_dwordx4 v[96:99], v[36:37], off offset:384
	global_load_dwordx4 v[100:103], v[34:35], off offset:384
	global_load_dwordx4 v[104:107], v[36:37], off offset:448
	global_load_dwordx4 v[108:111], v[34:35], off offset:448
	v_cndmask_b32_e32 v39, v197, v205, vcc
	v_cmp_eq_u32_e32 vcc, 0, v40
	s_waitcnt vmcnt(14)
	v_pk_fma_f32 v[28:29], v[28:29], v[52:53], v[48:49]
	s_nop 0
	v_mul_f32_e32 v44, v29, v29
	v_pk_fma_f32 v[30:31], v[30:31], v[54:55], v[50:51]
	v_fmac_f32_e32 v44, v28, v28
	global_store_dwordx4 v[34:35], v[28:31], off
	v_fmac_f32_e32 v44, v30, v30
	v_fmac_f32_e32 v44, v31, v31
	s_waitcnt vmcnt(12)
	v_pk_fma_f32 v[26:27], v[26:27], v[58:59], v[62:63]
	v_pk_fma_f32 v[24:25], v[24:25], v[56:57], v[60:61]
	global_store_dwordx4 v[34:35], v[24:27], off offset:64
	s_nop 1
	v_mul_f32_e32 v25, v25, v25
	v_fmac_f32_e32 v25, v24, v24
	v_fmac_f32_e32 v25, v26, v26
	v_fmac_f32_e32 v25, v27, v27
	v_add_f32_e32 v40, v44, v25
	s_waitcnt vmcnt(10)
	v_pk_fma_f32 v[22:23], v[22:23], v[66:67], v[70:71]
	v_pk_fma_f32 v[20:21], v[20:21], v[64:65], v[68:69]
	global_store_dwordx4 v[34:35], v[20:23], off offset:128
	s_nop 1
	v_mul_f32_e32 v21, v21, v21
	v_fmac_f32_e32 v21, v20, v20
	v_fmac_f32_e32 v21, v22, v22
	v_fmac_f32_e32 v21, v23, v23
	v_add_f32_e32 v28, v40, v21
	s_waitcnt vmcnt(8)
	v_pk_fma_f32 v[18:19], v[18:19], v[74:75], v[78:79]
	v_pk_fma_f32 v[16:17], v[16:17], v[72:73], v[76:77]
	global_store_dwordx4 v[34:35], v[16:19], off offset:192
	s_nop 1
	v_mul_f32_e32 v17, v17, v17
	v_fmac_f32_e32 v17, v16, v16
	v_fmac_f32_e32 v17, v18, v18
	v_fmac_f32_e32 v17, v19, v19
	v_add_f32_e32 v24, v28, v17
	s_waitcnt vmcnt(6)
	v_pk_fma_f32 v[14:15], v[14:15], v[82:83], v[86:87]
	v_pk_fma_f32 v[12:13], v[12:13], v[80:81], v[84:85]
	global_store_dwordx4 v[34:35], v[12:15], off offset:256
	s_nop 1
	v_mul_f32_e32 v13, v13, v13
	v_fmac_f32_e32 v13, v12, v12
	v_fmac_f32_e32 v13, v14, v14
	v_fmac_f32_e32 v13, v15, v15
	v_add_f32_e32 v20, v24, v13
	s_waitcnt vmcnt(4)
	v_pk_fma_f32 v[10:11], v[10:11], v[90:91], v[94:95]
	v_pk_fma_f32 v[8:9], v[8:9], v[88:89], v[92:93]
	global_store_dwordx4 v[34:35], v[8:11], off offset:320
	s_nop 1
	v_mul_f32_e32 v9, v9, v9
	v_fmac_f32_e32 v9, v8, v8
	v_fmac_f32_e32 v9, v10, v10
	v_fmac_f32_e32 v9, v11, v11
	v_add_f32_e32 v16, v20, v9
	s_waitcnt vmcnt(2)
	v_pk_fma_f32 v[6:7], v[6:7], v[98:99], v[102:103]
	v_pk_fma_f32 v[4:5], v[4:5], v[96:97], v[100:101]
	global_store_dwordx4 v[34:35], v[4:7], off offset:384
	s_nop 1
	v_mul_f32_e32 v5, v5, v5
	v_fmac_f32_e32 v5, v4, v4
	v_fmac_f32_e32 v5, v6, v6
	v_fmac_f32_e32 v5, v7, v7
	v_add_f32_e32 v12, v16, v5
	s_waitcnt vmcnt(0)
	v_pk_fma_f32 v[2:3], v[2:3], v[106:107], v[110:111]
	v_pk_fma_f32 v[0:1], v[0:1], v[104:105], v[108:109]
	global_store_dwordx4 v[34:35], v[0:3], off offset:448
	s_nop 1
	v_mul_f32_e32 v1, v1, v1
	v_fmac_f32_e32 v1, v0, v0
	v_fmac_f32_e32 v1, v2, v2
	v_fmac_f32_e32 v1, v3, v3
	v_add_f32_e32 v0, v12, v1
	v_lshlrev_b32_e32 v1, 2, v38
	ds_bpermute_b32 v1, v1, v0
	v_lshlrev_b32_e32 v2, 2, v39
	s_waitcnt lgkmcnt(0)
	v_add_f32_e32 v0, v0, v1
	ds_bpermute_b32 v1, v2, v0
	s_and_saveexec_b64 s[4:5], vcc
	s_cbranch_execz .LBB0_192
	v_lshlrev_b64 v[2:3], 5, v[32:33]
	v_lshl_add_u64 v[2:3], s[46:47], 0, v[2:3]
	s_lshl_b32 s78, s6, 2
	v_lshl_add_u64 v[2:3], v[2:3], 0, s[78:79]
	s_waitcnt lgkmcnt(0)
	v_add_f32_e32 v0, v0, v1
	global_store_dword v[2:3], v0, off

; __device__ __forceinline__ f32x4 mfma16(bf16x8 a, bf16x8 b, f32x4 c) { return __builtin_amdgcn_mfma_f32_16x16x32_bf16(a, b, c, 0, 0, 0); }
;     ...
;     for (int kt = 0; kt < nk; ++kt) {
;         lds_sync();
; #pragma unroll
;         for (int i = 0; i < 4; ++i) *(u32x4*)(sW + (srow + i * 32) * GST + skc) = rw[i];
;         lds_sync();
;         const int k0 = (kt + 1 < nk ? kt + 1 : kt) << 6;
;         const int ka = FRAG ? (k0 >> 5) * 512 : k0;
; #pragma unroll
;         for (int i = 0; i < 4; ++i) rw[i] = *(const u32x4*)(wp + (size_t)(i * 32) * ldw + k0);
;         bf16x8 wa[4], wb[4];
; #pragma unroll
;         for (int j = 0; j < 4; ++j) wa[j] = lds16(wr + (j * 16) * GST);
; #pragma unroll
;         for (int j = 0; j < 4; ++j) wb[j] = lds16(wr + ((j + 4) * 16) * GST);
;         __builtin_amdgcn_sched_barrier(0);
;         __builtin_amdgcn_s_setprio(1);
; #pragma unroll
;         for (int j = 0; j < 4; ++j)
; #pragma unroll
;             for (int i = 0; i < MI; ++i) acc[i][j] = mfma16(wa[j], __builtin_bit_cast(bf16x8, ra[i][0]), acc[i][j]);
;         __builtin_amdgcn_sched_barrier(0);
; #pragma unroll
;         for (int j = 0; j < 4; ++j) wa[j] = lds16(wr + (j * 16) * GST + 32);
;         __builtin_amdgcn_sched_barrier(0);
; #pragma unroll
;         for (int j = 0; j < 4; ++j)
; #pragma unroll
;             for (int i = 0; i < MI; ++i) acc[i][j + 4] = mfma16(wb[j], __builtin_bit_cast(bf16x8, ra[i][0]), acc[i][j + 4]);
;         __builtin_amdgcn_sched_barrier(0);
; #pragma unroll
;         for (int i = 0; i < MI; ++i) ra[i][0] = *(const u32x4*)(ap + (size_t)i * ASI + ka);
; #pragma unroll
;         for (int j = 0; j < 4; ++j) wb[j] = lds16(wr + ((j + 4) * 16) * GST + 32);
;         __builtin_amdgcn_sched_barrier(0);
; #pragma unroll
;         for (int j = 0; j < 4; ++j)
; #pragma unroll
;             for (int i = 0; i < MI; ++i) acc[i][j] = mfma16(wa[j], __builtin_bit_cast(bf16x8, ra[i][1]), acc[i][j]);
;         __builtin_amdgcn_sched_barrier(0);
; #pragma unroll
;         for (int j = 0; j < 4; ++j)
; #pragma unroll
;             for (int i = 0; i < MI; ++i) acc[i][j + 4] = mfma16(wb[j], __builtin_bit_cast(bf16x8, ra[i][1]), acc[i][j + 4]);
;         __builtin_amdgcn_s_setprio(0);
;         __builtin_amdgcn_sched_barrier(0);
; #pragma unroll
;         for (int i = 0; i < MI; ++i) ra[i][1] = *(const u32x4*)(ap + (size_t)i * ASI + ka + ASK);
;     }
.LBB0_218:
	s_cmpk_lg_i32 s5, 0xb00
	s_cselect_b32 s78, s5, 0xac0
	s_waitcnt vmcnt(63) expcnt(7) lgkmcnt(15)
	s_barrier
	s_waitcnt vmcnt(3)
	ds_write_b128 v61, v[48:51]
	s_waitcnt vmcnt(1)
	ds_write_b128 v61, v[52:55] offset:4608
	ds_write_b128 v61, v[40:43] offset:9216
	ds_write_b128 v61, v[44:47] offset:13824
	v_lshl_add_u64 v[40:41], s[78:79], 1, v[56:57]
	v_add_co_u32_e32 v42, vcc, s11, v40
	s_waitcnt lgkmcnt(0)
	s_nop 0
	v_addc_co_u32_e32 v43, vcc, 0, v41, vcc
	v_add_co_u32_e32 v44, vcc, s35, v40
	s_barrier
	s_nop 0
	v_addc_co_u32_e32 v45, vcc, 0, v41, vcc
	v_add_co_u32_e32 v46, vcc, s36, v40
	s_nop 1
	v_addc_co_u32_e32 v47, vcc, 0, v41, vcc
	global_load_dwordx4 v[48:51], v[40:41], off
	global_load_dwordx4 v[52:55], v[42:43], off
	s_nop 0
	global_load_dwordx4 v[40:43], v[44:45], off
	s_nop 0
	global_load_dwordx4 v[44:47], v[46:47], off
	ds_read_b128 v[62:65], v60
	ds_read_b128 v[66:69], v60 offset:2304
	ds_read_b128 v[70:73], v60 offset:4608
	ds_read_b128 v[74:77], v60 offset:6912
	ds_read_b128 v[78:81], v60 offset:9216
	ds_read_b128 v[82:85], v60 offset:11520
	ds_read_b128 v[86:89], v60 offset:13824
	ds_read_b128 v[90:93], v60 offset:16128
	s_setprio 1
	s_waitcnt lgkmcnt(7)
	v_mfma_f32_16x16x32_bf16 v[28:31], v[62:65], v[36:39], v[28:31]
	s_waitcnt lgkmcnt(6)
	v_mfma_f32_16x16x32_bf16 v[24:27], v[66:69], v[36:39], v[24:27]
	s_waitcnt lgkmcnt(5)
	v_mfma_f32_16x16x32_bf16 v[20:23], v[70:73], v[36:39], v[20:23]
	s_waitcnt lgkmcnt(4)
	v_mfma_f32_16x16x32_bf16 v[16:19], v[74:77], v[36:39], v[16:19]
	ds_read_b128 v[62:65], v60 offset:64
	ds_read_b128 v[66:69], v60 offset:2368
	ds_read_b128 v[70:73], v60 offset:4672
	ds_read_b128 v[74:77], v60 offset:6976
	s_waitcnt lgkmcnt(7)
	v_mfma_f32_16x16x32_bf16 v[12:15], v[78:81], v[36:39], v[12:15]
	s_waitcnt lgkmcnt(6)
	v_mfma_f32_16x16x32_bf16 v[8:11], v[82:85], v[36:39], v[8:11]
	s_waitcnt lgkmcnt(5)
	v_mfma_f32_16x16x32_bf16 v[4:7], v[86:89], v[36:39], v[4:7]
	s_waitcnt lgkmcnt(4)
	v_mfma_f32_16x16x32_bf16 v[0:3], v[90:93], v[36:39], v[0:3]
	s_lshl_b32 s78, s78, 5
	v_lshl_add_u64 v[94:95], v[58:59], 0, s[78:79]
	global_load_dwordx4 v[36:39], v[94:95], off
	ds_read_b128 v[78:81], v60 offset:9280
	ds_read_b128 v[82:85], v60 offset:11584
	ds_read_b128 v[86:89], v60 offset:13888
	ds_read_b128 v[90:93], v60 offset:16192
	s_waitcnt vmcnt(5) lgkmcnt(7)
	v_mfma_f32_16x16x32_bf16 v[28:31], v[62:65], v[32:35], v[28:31]
	s_waitcnt lgkmcnt(6)
	v_mfma_f32_16x16x32_bf16 v[24:27], v[66:69], v[32:35], v[24:27]
	s_waitcnt lgkmcnt(5)
	v_mfma_f32_16x16x32_bf16 v[20:23], v[70:73], v[32:35], v[20:23]
	s_waitcnt lgkmcnt(4)
	v_mfma_f32_16x16x32_bf16 v[16:19], v[74:77], v[32:35], v[16:19]
	s_waitcnt lgkmcnt(3)
	v_mfma_f32_16x16x32_bf16 v[12:15], v[78:81], v[32:35], v[12:15]
	s_waitcnt lgkmcnt(2)
	v_mfma_f32_16x16x32_bf16 v[8:11], v[82:85], v[32:35], v[8:11]
	s_waitcnt lgkmcnt(1)
	v_mfma_f32_16x16x32_bf16 v[4:7], v[86:89], v[32:35], v[4:7]
	s_waitcnt lgkmcnt(0)
	v_mfma_f32_16x16x32_bf16 v[0:3], v[90:93], v[32:35], v[0:3]
	s_setprio 0
	global_load_dwordx4 v[32:35], v[94:95], off offset:1024
	s_add_i32 s5, s5, 64
	s_cmpk_lg_i32 s5, 0xb40
	s_cbranch_scc1 .LBB0_218
; __device__ __forceinline__ int tid_() { int t = threadIdx.x; asm volatile("" : "+v"(t)); return t; }
; template <int MI>
; __device__ __forceinline__ void epi_resid(CParams& p, int m0, int n0, const f32x4 (&acc)[MI][8], const float* gate  ) {
;     const int lane = tid_() & 63, wave = tid_() >> 6, l16 = lane & 15, quad = lane >> 4;
; #pragma unroll
;     for (int i = 0; i < MI; ++i) {
;         const int row = m0 + wave * 16 * MI + i * 16 + l16;
;         float* xr = xrow(p, row);
;         const float* g = gate + (size_t)seg_of(row) * 6144;
;         float ss = 0.f;
; #pragma unroll
;         for (int j = 0; j < 8; ++j) {
;             const int col = n0 + j * 16 + quad * 4;
;             const f32x4 gv = *(const f32x4*)(g + col);
;             f32x4 xv = *(f32x4*)(xr + col);
;             xv += gv * acc[i][j];
;             *(f32x4*)(xr + col) = xv;
;             ss += xv[0] * xv[0] + xv[1] * xv[1] + xv[2] * xv[2] + xv[3] * xv[3];
;         }
;         ss += __shfl_xor(ss, 16); ss += __shfl_xor(ss, 32);
;         if (quad == 0) ((float*)(p.ws + WS_PART))[(size_t)row * 8 + (n0 >> 7)] = ss;
;         __builtin_amdgcn_sched_barrier(0);
;     }
; }
	s_waitcnt vmcnt(0)
	v_mov_b32_e32 v32, v167
	v_mov_b32_e32 v33, v167
	v_mov_b32_e32 v36, s16
	v_ashrrev_i32_e32 v33, 2, v33
	v_bfe_u32 v40, v32, 4, 2
	v_and_b32_e32 v33, -16, v33
	v_and_or_b32 v32, v32, 15, s4
	v_add_u32_e32 v32, v33, v32
	v_cmp_gt_i32_e64 s[42:43], s34, v32
	v_subrev_co_u32_e32 v34, vcc, 0x4000, v32
	v_ashrrev_i32_e32 v33, 31, v32
	v_mov_b32_e32 v37, s45
	v_cndmask_b32_e64 v35, 0, v33, s[42:43]
	v_cndmask_b32_e64 v34, v34, v32, s[42:43]
	v_cndmask_b32_e64 v37, v36, v37, s[42:43]
	v_mov_b32_e32 v36, s15
	v_mov_b32_e32 v38, s44
	v_cndmask_b32_e64 v36, v36, v38, s[42:43]
	v_lshlrev_b64 v[34:35], 12, v[34:35]
	s_movk_i32 s2, 0x1fff
	v_lshl_add_u64 v[34:35], v[36:37], 0, v[34:35]
	v_cndmask_b32_e32 v36, v213, v214, vcc
	v_cmp_lt_i32_e32 vcc, s2, v32
	s_lshl_b32 s4, s6, 9
	s_nop 0
	v_cndmask_b32_e32 v36, 0, v36, vcc
	v_lshlrev_b32_e32 v164, 2, v36
	v_lshl_add_u64 v[36:37], s[48:49], 0, v[164:165]
	v_cmp_lt_i32_e32 vcc, v204, v199
	v_lshl_or_b32 v164, v40, 4, s4
	v_lshl_add_u64 v[36:37], v[36:37], 0, v[164:165]
	v_cndmask_b32_e32 v38, v197, v204, vcc
	v_cmp_lt_i32_e32 vcc, v205, v199
	v_lshl_add_u64 v[34:35], v[34:35], 0, v[164:165]
	global_load_dwordx4 v[48:51], v[34:35], off
	global_load_dwordx4 v[52:55], v[36:37], off
	global_load_dwordx4 v[56:59], v[36:37], off offset:64
	global_load_dwordx4 v[60:63], v[34:35], off offset:64
	global_load_dwordx4 v[64:67], v[36:37], off offset:128
	global_load_dwordx4 v[68:71], v[34:35], off offset:128
	global_load_dwordx4 v[72:75], v[36:37], off offset:192
	global_load_dwordx4 v[76:79], v[34:35], off offset:192
	global_load_dwordx4 v[80:83], v[36:37], off offset:256
	global_load_dwordx4 v[84:87], v[34:35], off offset:256
	global_load_dwordx4 v[88:91], v[36:37], off offset:320
	global_load_dwordx4 v[92:95], v[34:35], off offset:320
	global_load_dwordx4 v[96:99], v[36:37], off offset:384
	global_load_dwordx4 v[100:103], v[34:35], off offset:384
	global_load_dwordx4 v[104:107], v[36:37], off offset:448
	global_load_dwordx4 v[108:111], v[34:35], off offset:448
	v_cndmask_b32_e32 v39, v197, v205, vcc
	v_cmp_eq_u32_e32 vcc, 0, v40
	s_waitcnt vmcnt(14)
	v_pk_fma_f32 v[28:29], v[28:29], v[52:53], v[48:49]
	s_nop 0
	v_mul_f32_e32 v44, v29, v29
	v_pk_fma_f32 v[30:31], v[30:31], v[54:55], v[50:51]
	v_fmac_f32_e32 v44, v28, v28
	global_store_dwordx4 v[34:35], v[28:31], off
	v_fmac_f32_e32 v44, v30, v30
	v_fmac_f32_e32 v44, v31, v31
	s_waitcnt vmcnt(12)
	v_pk_fma_f32 v[26:27], v[26:27], v[58:59], v[62:63]
	v_pk_fma_f32 v[24:25], v[24:25], v[56:57], v[60:61]
	global_store_dwordx4 v[34:35], v[24:27], off offset:64
	s_nop 1
	v_mul_f32_e32 v25, v25, v25
	v_fmac_f32_e32 v25, v24, v24
	v_fmac_f32_e32 v25, v26, v26
	v_fmac_f32_e32 v25, v27, v27
	v_add_f32_e32 v40, v44, v25
	s_waitcnt vmcnt(10)
	v_pk_fma_f32 v[22:23], v[22:23], v[66:67], v[70:71]
	v_pk_fma_f32 v[20:21], v[20:21], v[64:65], v[68:69]
	global_store_dwordx4 v[34:35], v[20:23], off offset:128
	s_nop 1
	v_mul_f32_e32 v21, v21, v21
	v_fmac_f32_e32 v21, v20, v20
	v_fmac_f32_e32 v21, v22, v22
	v_fmac_f32_e32 v21, v23, v23
	v_add_f32_e32 v28, v40, v21
	s_waitcnt vmcnt(8)
	v_pk_fma_f32 v[18:19], v[18:19], v[74:75], v[78:79]
	v_pk_fma_f32 v[16:17], v[16:17], v[72:73], v[76:77]
	global_store_dwordx4 v[34:35], v[16:19], off offset:192
	s_nop 1
	v_mul_f32_e32 v17, v17, v17
	v_fmac_f32_e32 v17, v16, v16
	v_fmac_f32_e32 v17, v18, v18
	v_fmac_f32_e32 v17, v19, v19
	v_add_f32_e32 v24, v28, v17
	s_waitcnt vmcnt(6)
	v_pk_fma_f32 v[14:15], v[14:15], v[82:83], v[86:87]
	v_pk_fma_f32 v[12:13], v[12:13], v[80:81], v[84:85]
	global_store_dwordx4 v[34:35], v[12:15], off offset:256
	s_nop 1
	v_mul_f32_e32 v13, v13, v13
	v_fmac_f32_e32 v13, v12, v12
	v_fmac_f32_e32 v13, v14, v14
	v_fmac_f32_e32 v13, v15, v15
	v_add_f32_e32 v20, v24, v13
	s_waitcnt vmcnt(4)
	v_pk_fma_f32 v[10:11], v[10:11], v[90:91], v[94:95]
	v_pk_fma_f32 v[8:9], v[8:9], v[88:89], v[92:93]
	global_store_dwordx4 v[34:35], v[8:11], off offset:320
	s_nop 1
	v_mul_f32_e32 v9, v9, v9
	v_fmac_f32_e32 v9, v8, v8
	v_fmac_f32_e32 v9, v10, v10
	v_fmac_f32_e32 v9, v11, v11
	v_add_f32_e32 v16, v20, v9
	s_waitcnt vmcnt(2)
	v_pk_fma_f32 v[6:7], v[6:7], v[98:99], v[102:103]
	v_pk_fma_f32 v[4:5], v[4:5], v[96:97], v[100:101]
	global_store_dwordx4 v[34:35], v[4:7], off offset:384
	s_nop 1
	v_mul_f32_e32 v5, v5, v5
	v_fmac_f32_e32 v5, v4, v4
	v_fmac_f32_e32 v5, v6, v6
	v_fmac_f32_e32 v5, v7, v7
	v_add_f32_e32 v12, v16, v5
	s_waitcnt vmcnt(0)
	v_pk_fma_f32 v[2:3], v[2:3], v[106:107], v[110:111]
	v_pk_fma_f32 v[0:1], v[0:1], v[104:105], v[108:109]
	global_store_dwordx4 v[34:35], v[0:3], off offset:448
	s_nop 1
	v_mul_f32_e32 v1, v1, v1
	v_fmac_f32_e32 v1, v0, v0
	v_fmac_f32_e32 v1, v2, v2
	v_fmac_f32_e32 v1, v3, v3
	v_add_f32_e32 v0, v12, v1
	v_lshlrev_b32_e32 v1, 2, v38
	ds_bpermute_b32 v1, v1, v0
	v_lshlrev_b32_e32 v2, 2, v39
	s_waitcnt lgkmcnt(0)
	v_add_f32_e32 v0, v0, v1
	ds_bpermute_b32 v1, v2, v0
	s_and_saveexec_b64 s[4:5], vcc
	s_cbranch_execz .LBB0_221
	v_lshlrev_b64 v[2:3], 5, v[32:33]
	v_lshl_add_u64 v[2:3], s[46:47], 0, v[2:3]
	s_lshl_b32 s78, s6, 2
	v_lshl_add_u64 v[2:3], v[2:3], 0, s[78:79]
	s_waitcnt lgkmcnt(0)
	v_add_f32_e32 v0, v0, v1
	global_store_dword v[2:3], v0, off

; __device__ __forceinline__ f32x4 mfma16(bf16x8 a, bf16x8 b, f32x4 c) { return __builtin_amdgcn_mfma_f32_16x16x32_bf16(a, b, c, 0, 0, 0); }
;     ...
;     for (int kt = 0; kt < nk; ++kt) {
;         lds_sync();
; #pragma unroll
;         for (int i = 0; i < 4; ++i) *(u32x4*)(sW + (srow + i * 32) * GST + skc) = rw[i];
;         lds_sync();
;         const int k0 = (kt + 1 < nk ? kt + 1 : kt) << 6;
;         const int ka = FRAG ? (k0 >> 5) * 512 : k0;
; #pragma unroll
;         for (int i = 0; i < 4; ++i) rw[i] = *(const u32x4*)(wp + (size_t)(i * 32) * ldw + k0);
;         bf16x8 wa[4], wb[4];
; #pragma unroll
;         for (int j = 0; j < 4; ++j) wa[j] = lds16(wr + (j * 16) * GST);
; #pragma unroll
;         for (int j = 0; j < 4; ++j) wb[j] = lds16(wr + ((j + 4) * 16) * GST);
;         __builtin_amdgcn_sched_barrier(0);
;         __builtin_amdgcn_s_setprio(1);
; #pragma unroll
;         for (int j = 0; j < 4; ++j)
; #pragma unroll
;             for (int i = 0; i < MI; ++i) acc[i][j] = mfma16(wa[j], __builtin_bit_cast(bf16x8, ra[i][0]), acc[i][j]);
;         __builtin_amdgcn_sched_barrier(0);
; #pragma unroll
;         for (int j = 0; j < 4; ++j) wa[j] = lds16(wr + (j * 16) * GST + 32);
;         __builtin_amdgcn_sched_barrier(0);
; #pragma unroll
;         for (int j = 0; j < 4; ++j)
; #pragma unroll
;             for (int i = 0; i < MI; ++i) acc[i][j + 4] = mfma16(wb[j], __builtin_bit_cast(bf16x8, ra[i][0]), acc[i][j + 4]);
;         __builtin_amdgcn_sched_barrier(0);
; #pragma unroll
;         for (int i = 0; i < MI; ++i) ra[i][0] = *(const u32x4*)(ap + (size_t)i * ASI + ka);
; #pragma unroll
;         for (int j = 0; j < 4; ++j) wb[j] = lds16(wr + ((j + 4) * 16) * GST + 32);
;         __builtin_amdgcn_sched_barrier(0);
; #pragma unroll
;         for (int j = 0; j < 4; ++j)
; #pragma unroll
;             for (int i = 0; i < MI; ++i) acc[i][j] = mfma16(wa[j], __builtin_bit_cast(bf16x8, ra[i][1]), acc[i][j]);
;         __builtin_amdgcn_sched_barrier(0);
; #pragma unroll
;         for (int j = 0; j < 4; ++j)
; #pragma unroll
;             for (int i = 0; i < MI; ++i) acc[i][j + 4] = mfma16(wb[j], __builtin_bit_cast(bf16x8, ra[i][1]), acc[i][j + 4]);
;         __builtin_amdgcn_s_setprio(0);
;         __builtin_amdgcn_sched_barrier(0);
; #pragma unroll
;         for (int i = 0; i < MI; ++i) ra[i][1] = *(const u32x4*)(ap + (size_t)i * ASI + ka + ASK);
;     }
.LBB0_519:
	s_cmpk_lg_i32 s5, 0x800
	s_cselect_b32 s78, s5, 0x7c0
	s_barrier
	s_waitcnt vmcnt(3)
	ds_write_b128 v61, v[48:51]
	s_waitcnt vmcnt(1)
	ds_write_b128 v61, v[52:55] offset:4608
	ds_write_b128 v61, v[40:43] offset:9216
	ds_write_b128 v61, v[44:47] offset:13824
	v_lshl_add_u64 v[40:41], s[78:79], 1, v[56:57]
	v_add_co_u32_e32 v42, vcc, s80, v40
	s_waitcnt lgkmcnt(0)
	s_nop 0
	v_addc_co_u32_e32 v43, vcc, 0, v41, vcc
	v_add_co_u32_e32 v44, vcc, s82, v40
	s_barrier
	s_nop 0
	v_addc_co_u32_e32 v45, vcc, 0, v41, vcc
	v_add_co_u32_e32 v46, vcc, s83, v40
	s_nop 1
	v_addc_co_u32_e32 v47, vcc, 0, v41, vcc
	global_load_dwordx4 v[48:51], v[40:41], off
	global_load_dwordx4 v[52:55], v[42:43], off
	s_nop 0
	global_load_dwordx4 v[40:43], v[44:45], off
	s_nop 0
	global_load_dwordx4 v[44:47], v[46:47], off
	ds_read_b128 v[62:65], v60
	ds_read_b128 v[66:69], v60 offset:2304
	ds_read_b128 v[70:73], v60 offset:4608
	ds_read_b128 v[74:77], v60 offset:6912
	ds_read_b128 v[78:81], v60 offset:9216
	ds_read_b128 v[82:85], v60 offset:11520
	ds_read_b128 v[86:89], v60 offset:13824
	ds_read_b128 v[90:93], v60 offset:16128
	s_setprio 1
	s_waitcnt lgkmcnt(7)
	v_mfma_f32_16x16x32_bf16 v[28:31], v[62:65], v[36:39], v[28:31]
	s_waitcnt lgkmcnt(6)
	v_mfma_f32_16x16x32_bf16 v[24:27], v[66:69], v[36:39], v[24:27]
	s_waitcnt lgkmcnt(5)
	v_mfma_f32_16x16x32_bf16 v[20:23], v[70:73], v[36:39], v[20:23]
	s_waitcnt lgkmcnt(4)
	v_mfma_f32_16x16x32_bf16 v[16:19], v[74:77], v[36:39], v[16:19]
	ds_read_b128 v[62:65], v60 offset:64
	ds_read_b128 v[66:69], v60 offset:2368
	ds_read_b128 v[70:73], v60 offset:4672
	ds_read_b128 v[74:77], v60 offset:6976
	s_waitcnt lgkmcnt(7)
	v_mfma_f32_16x16x32_bf16 v[12:15], v[78:81], v[36:39], v[12:15]
	s_waitcnt lgkmcnt(6)
	v_mfma_f32_16x16x32_bf16 v[8:11], v[82:85], v[36:39], v[8:11]
	s_waitcnt lgkmcnt(5)
	v_mfma_f32_16x16x32_bf16 v[4:7], v[86:89], v[36:39], v[4:7]
	s_waitcnt lgkmcnt(4)
	v_mfma_f32_16x16x32_bf16 v[0:3], v[90:93], v[36:39], v[0:3]
	s_lshl_b32 s78, s78, 5
	v_lshl_add_u64 v[94:95], v[58:59], 0, s[78:79]
	global_load_dwordx4 v[36:39], v[94:95], off
	ds_read_b128 v[78:81], v60 offset:9280
	ds_read_b128 v[82:85], v60 offset:11584
	ds_read_b128 v[86:89], v60 offset:13888
	ds_read_b128 v[90:93], v60 offset:16192
	s_waitcnt vmcnt(5) lgkmcnt(7)
	v_mfma_f32_16x16x32_bf16 v[28:31], v[62:65], v[32:35], v[28:31]
	s_waitcnt lgkmcnt(6)
	v_mfma_f32_16x16x32_bf16 v[24:27], v[66:69], v[32:35], v[24:27]
	s_waitcnt lgkmcnt(5)
	v_mfma_f32_16x16x32_bf16 v[20:23], v[70:73], v[32:35], v[20:23]
	s_waitcnt lgkmcnt(4)
	v_mfma_f32_16x16x32_bf16 v[16:19], v[74:77], v[32:35], v[16:19]
	s_waitcnt lgkmcnt(3)
	v_mfma_f32_16x16x32_bf16 v[12:15], v[78:81], v[32:35], v[12:15]
	s_waitcnt lgkmcnt(2)
	v_mfma_f32_16x16x32_bf16 v[8:11], v[82:85], v[32:35], v[8:11]
	s_waitcnt lgkmcnt(1)
	v_mfma_f32_16x16x32_bf16 v[4:7], v[86:89], v[32:35], v[4:7]
	s_waitcnt lgkmcnt(0)
	v_mfma_f32_16x16x32_bf16 v[0:3], v[90:93], v[32:35], v[0:3]
	s_setprio 0
	global_load_dwordx4 v[32:35], v[94:95], off offset:1024
	s_add_i32 s5, s5, 64
	s_cmpk_lg_i32 s5, 0x840
	s_cbranch_scc1 .LBB0_519
; __device__ __forceinline__ int tid_() { int t = threadIdx.x; asm volatile("" : "+v"(t)); return t; }
; template <int MI>
; __device__ __forceinline__ void epi_resid(CParams& p, int m0, int n0, const f32x4 (&acc)[MI][8], const float* gate  ) {
;     const int lane = tid_() & 63, wave = tid_() >> 6, l16 = lane & 15, quad = lane >> 4;
; #pragma unroll
;     for (int i = 0; i < MI; ++i) {
;         const int row = m0 + wave * 16 * MI + i * 16 + l16;
;         float* xr = xrow(p, row);
;         const float* g = gate + (size_t)seg_of(row) * 6144;
;         float ss = 0.f;
; #pragma unroll
;         for (int j = 0; j < 8; ++j) {
;             const int col = n0 + j * 16 + quad * 4;
;             const f32x4 gv = *(const f32x4*)(g + col);
;             f32x4 xv = *(f32x4*)(xr + col);
;             xv += gv * acc[i][j];
;             *(f32x4*)(xr + col) = xv;
;             ss += xv[0] * xv[0] + xv[1] * xv[1] + xv[2] * xv[2] + xv[3] * xv[3];
;         }
;         ss += __shfl_xor(ss, 16); ss += __shfl_xor(ss, 32);
;         if (quad == 0) ((float*)(p.ws + WS_PART))[(size_t)row * 8 + (n0 >> 7)] = ss;
;         __builtin_amdgcn_sched_barrier(0);
;     }
; }
	s_waitcnt vmcnt(0)
	v_mov_b32_e32 v32, v167
	v_mov_b32_e32 v33, v167
	v_mov_b32_e32 v36, s16
	v_ashrrev_i32_e32 v33, 2, v33
	v_bfe_u32 v40, v32, 4, 2
	v_and_b32_e32 v33, -16, v33
	v_and_or_b32 v32, v32, 15, s4
	v_add_u32_e32 v32, v33, v32
	v_cmp_gt_i32_e64 s[42:43], s34, v32
	v_subrev_co_u32_e32 v34, vcc, 0x4000, v32
	v_ashrrev_i32_e32 v33, 31, v32
	v_mov_b32_e32 v37, s45
	v_cndmask_b32_e64 v35, 0, v33, s[42:43]
	v_cndmask_b32_e64 v34, v34, v32, s[42:43]
	v_cndmask_b32_e64 v37, v36, v37, s[42:43]
	v_mov_b32_e32 v36, s15
	v_mov_b32_e32 v38, s44
	v_cndmask_b32_e64 v36, v36, v38, s[42:43]
	v_lshlrev_b64 v[34:35], 12, v[34:35]
	s_movk_i32 s2, 0x1fff
	v_lshl_add_u64 v[34:35], v[36:37], 0, v[34:35]
	v_cndmask_b32_e32 v36, v213, v214, vcc
	v_cmp_lt_i32_e32 vcc, s2, v32
	s_lshl_b32 s4, s6, 9
	s_nop 0
	v_cndmask_b32_e32 v36, 0, v36, vcc
	v_lshlrev_b32_e32 v164, 2, v36
	v_lshl_add_u64 v[36:37], s[48:49], 0, v[164:165]
	v_cmp_lt_i32_e32 vcc, v204, v199
	v_lshl_or_b32 v164, v40, 4, s4
	v_lshl_add_u64 v[36:37], v[36:37], 0, v[164:165]
	v_cndmask_b32_e32 v38, v197, v204, vcc
	v_cmp_lt_i32_e32 vcc, v205, v199
	v_lshl_add_u64 v[34:35], v[34:35], 0, v[164:165]
	global_load_dwordx4 v[48:51], v[34:35], off
	global_load_dwordx4 v[52:55], v[36:37], off
	global_load_dwordx4 v[56:59], v[36:37], off offset:64
	global_load_dwordx4 v[60:63], v[34:35], off offset:64
	global_load_dwordx4 v[64:67], v[36:37], off offset:128
	global_load_dwordx4 v[68:71], v[34:35], off offset:128
	global_load_dwordx4 v[72:75], v[36:37], off offset:192
	global_load_dwordx4 v[76:79], v[34:35], off offset:192
	global_load_dwordx4 v[80:83], v[36:37], off offset:256
	global_load_dwordx4 v[84:87], v[34:35], off offset:256
	global_load_dwordx4 v[88:91], v[36:37], off offset:320
	global_load_dwordx4 v[92:95], v[34:35], off offset:320
	global_load_dwordx4 v[96:99], v[36:37], off offset:384
	global_load_dwordx4 v[100:103], v[34:35], off offset:384
	global_load_dwordx4 v[104:107], v[36:37], off offset:448
	global_load_dwordx4 v[108:111], v[34:35], off offset:448
	v_cndmask_b32_e32 v39, v197, v205, vcc
	v_cmp_eq_u32_e32 vcc, 0, v40
	s_waitcnt vmcnt(14)
	v_pk_fma_f32 v[28:29], v[28:29], v[52:53], v[48:49]
	s_nop 0
	v_mul_f32_e32 v44, v29, v29
	v_pk_fma_f32 v[30:31], v[30:31], v[54:55], v[50:51]
	v_fmac_f32_e32 v44, v28, v28
	global_store_dwordx4 v[34:35], v[28:31], off
	v_fmac_f32_e32 v44, v30, v30
	v_fmac_f32_e32 v44, v31, v31
	s_waitcnt vmcnt(12)
	v_pk_fma_f32 v[26:27], v[26:27], v[58:59], v[62:63]
	v_pk_fma_f32 v[24:25], v[24:25], v[56:57], v[60:61]
	global_store_dwordx4 v[34:35], v[24:27], off offset:64
	s_nop 1
	v_mul_f32_e32 v25, v25, v25
	v_fmac_f32_e32 v25, v24, v24
	v_fmac_f32_e32 v25, v26, v26
	v_fmac_f32_e32 v25, v27, v27
	v_add_f32_e32 v40, v44, v25
	s_waitcnt vmcnt(10)
	v_pk_fma_f32 v[22:23], v[22:23], v[66:67], v[70:71]
	v_pk_fma_f32 v[20:21], v[20:21], v[64:65], v[68:69]
	global_store_dwordx4 v[34:35], v[20:23], off offset:128
	s_nop 1
	v_mul_f32_e32 v21, v21, v21
	v_fmac_f32_e32 v21, v20, v20
	v_fmac_f32_e32 v21, v22, v22
	v_fmac_f32_e32 v21, v23, v23
	v_add_f32_e32 v28, v40, v21
	s_waitcnt vmcnt(8)
	v_pk_fma_f32 v[18:19], v[18:19], v[74:75], v[78:79]
	v_pk_fma_f32 v[16:17], v[16:17], v[72:73], v[76:77]
	global_store_dwordx4 v[34:35], v[16:19], off offset:192
	s_nop 1
	v_mul_f32_e32 v17, v17, v17
	v_fmac_f32_e32 v17, v16, v16
	v_fmac_f32_e32 v17, v18, v18
	v_fmac_f32_e32 v17, v19, v19
	v_add_f32_e32 v24, v28, v17
	s_waitcnt vmcnt(6)
	v_pk_fma_f32 v[14:15], v[14:15], v[82:83], v[86:87]
	v_pk_fma_f32 v[12:13], v[12:13], v[80:81], v[84:85]
	global_store_dwordx4 v[34:35], v[12:15], off offset:256
	s_nop 1
	v_mul_f32_e32 v13, v13, v13
	v_fmac_f32_e32 v13, v12, v12
	v_fmac_f32_e32 v13, v14, v14
	v_fmac_f32_e32 v13, v15, v15
	v_add_f32_e32 v20, v24, v13
	s_waitcnt vmcnt(4)
	v_pk_fma_f32 v[10:11], v[10:11], v[90:91], v[94:95]
	v_pk_fma_f32 v[8:9], v[8:9], v[88:89], v[92:93]
	global_store_dwordx4 v[34:35], v[8:11], off offset:320
	s_nop 1
	v_mul_f32_e32 v9, v9, v9
	v_fmac_f32_e32 v9, v8, v8
	v_fmac_f32_e32 v9, v10, v10
	v_fmac_f32_e32 v9, v11, v11
	v_add_f32_e32 v16, v20, v9
	s_waitcnt vmcnt(2)
	v_pk_fma_f32 v[6:7], v[6:7], v[98:99], v[102:103]
	v_pk_fma_f32 v[4:5], v[4:5], v[96:97], v[100:101]
	global_store_dwordx4 v[34:35], v[4:7], off offset:384
	s_nop 1
	v_mul_f32_e32 v5, v5, v5
	v_fmac_f32_e32 v5, v4, v4
	v_fmac_f32_e32 v5, v6, v6
	v_fmac_f32_e32 v5, v7, v7
	v_add_f32_e32 v12, v16, v5
	s_waitcnt vmcnt(0)
	v_pk_fma_f32 v[2:3], v[2:3], v[106:107], v[110:111]
	v_pk_fma_f32 v[0:1], v[0:1], v[104:105], v[108:109]
	global_store_dwordx4 v[34:35], v[0:3], off offset:448
	s_nop 1
	v_mul_f32_e32 v1, v1, v1
	v_fmac_f32_e32 v1, v0, v0
	v_fmac_f32_e32 v1, v2, v2
	v_fmac_f32_e32 v1, v3, v3
	v_add_f32_e32 v0, v12, v1
	v_lshlrev_b32_e32 v1, 2, v38
	ds_bpermute_b32 v1, v1, v0
	v_lshlrev_b32_e32 v2, 2, v39
	s_waitcnt lgkmcnt(0)
	v_add_f32_e32 v0, v0, v1
	ds_bpermute_b32 v1, v2, v0
	s_and_saveexec_b64 s[4:5], vcc
	s_cbranch_execz .LBB0_522
	v_lshlrev_b64 v[2:3], 5, v[32:33]
	v_lshl_add_u64 v[2:3], s[46:47], 0, v[2:3]
	s_lshl_b32 s78, s6, 2
	v_lshl_add_u64 v[2:3], v[2:3], 0, s[78:79]
	s_waitcnt lgkmcnt(0)
	v_add_f32_e32 v0, v0, v1
	global_store_dword v[2:3], v0, off
